# mix1 knorm items: butterflies of 4 row pairs interleaved (12 instead of 48 serial ds_bpermute round trips per 16-row batch), same per-pair op order; on top of v41
# baseline (speedup 1.0000x reference)
; __device__ __forceinline__ float bf2f(unsigned short u) { return __uint_as_float((unsigned)u << 16); }
; __device__ __forceinline__ void knorm_item(const KArgs& a, int l, int item, int wave, int lane) {
;     ...
;     for (int r0 = 0; r0 < 128; r0 += 16) {
;         float v[16];
; #pragma unroll
;         for (int i = 0; i < 16; ++i) { const int task = item * 1024 + wave * 128 + r0 + i, row = task >> 2, which = (task >> 1) & 1, g = task & 1;
;             v[i] = bf2f(Z[(size_t)row * ZW + (which ? ZC_KW : ZC_KS) + g * 64 + lane]); }
; #pragma unroll
;         for (int i = 0; i < 16; ++i) { const int task = item * 1024 + wave * 128 + r0 + i, row = task >> 2, which = (task >> 1) & 1, g = task & 1;
;             const float rstd = rsqrtf(wave_sum(v[i] * v[i]) * (1.f / 64.f) + EPS);
.LBB0_237:
	s_add_i32 s0, s24, s57
	s_add_i32 s0, s0, 0xfff80010
	s_ashr_i32 s4, s0, 2
	s_ashr_i32 s5, s4, 31
	s_mul_i32 s0, s4, 0x1a00
	s_mul_hi_i32 s1, s4, 0x1a00
	s_add_u32 s0, s92, s0
	s_addc_u32 s1, s93, s1
	v_lshl_add_u64 v[0:1], s[0:1], 0, v[64:65]
	v_add_co_u32_e32 v0, vcc, s47, v0
	s_or_b32 s28, s4, 1
	s_nop 0
	v_addc_co_u32_e32 v1, vcc, 0, v1, vcc
	global_load_ushort v4, v[0:1], off offset:1024
	global_load_ushort v6, v[0:1], off offset:1152
	global_load_ushort v27, v[0:1], off offset:1536
	global_load_ushort v28, v[0:1], off offset:1664
	s_ashr_i32 s29, s28, 31
	s_mul_i32 s0, s28, 0x1a00
	s_mul_hi_i32 s1, s28, 0x1a00
	s_add_u32 s0, s92, s0
	s_addc_u32 s1, s93, s1
	s_or_b32 s26, s4, 2
	v_lshl_add_u64 v[0:1], s[0:1], 0, v[64:65]
	s_ashr_i32 s27, s26, 31
	s_mul_i32 s0, s26, 0x1a00
	v_add_co_u32_e32 v0, vcc, s47, v0
	s_mul_hi_i32 s1, s26, 0x1a00
	s_add_u32 s0, s92, s0
	v_addc_co_u32_e32 v1, vcc, 0, v1, vcc
	s_addc_u32 s1, s93, s1
	global_load_ushort v25, v[0:1], off offset:1024
	global_load_ushort v26, v[0:1], off offset:1152
	global_load_ushort v23, v[0:1], off offset:1536
	global_load_ushort v24, v[0:1], off offset:1664
	v_lshl_add_u64 v[0:1], s[0:1], 0, v[64:65]
	s_or_b32 s0, s4, 3
	s_ashr_i32 s1, s0, 31
	s_mul_i32 s30, s0, 0x1a00
	v_add_co_u32_e32 v0, vcc, s47, v0
	s_mul_hi_i32 s31, s0, 0x1a00
	s_add_u32 s30, s92, s30
	v_addc_co_u32_e32 v1, vcc, 0, v1, vcc
	s_addc_u32 s31, s93, s31
	global_load_ushort v21, v[0:1], off offset:1024
	global_load_ushort v22, v[0:1], off offset:1152
	global_load_ushort v19, v[0:1], off offset:1536
	global_load_ushort v20, v[0:1], off offset:1664
	v_lshl_add_u64 v[0:1], s[30:31], 0, v[64:65]
	v_add_co_u32_e32 v0, vcc, s47, v0
	s_lshl_b64 s[30:31], s[4:5], 8
	s_nop 0
	v_addc_co_u32_e32 v1, vcc, 0, v1, vcc
	global_load_ushort v17, v[0:1], off offset:1024
	global_load_ushort v18, v[0:1], off offset:1152
	global_load_ushort v15, v[0:1], off offset:1536
	global_load_ushort v16, v[0:1], off offset:1664
	v_lshl_add_u64 v[2:3], v[68:69], 0, s[30:31]
	s_lshl_b64 s[28:29], s[28:29], 8
	s_lshl_b64 s[26:27], s[26:27], 8
	s_lshl_b64 s[0:1], s[0:1], 8
	s_add_i32 s57, s57, 16
	s_cmpk_gt_u32 s57, 0x6f
	v_mov_b64_e32 v[0:1], s[20:21]
	s_waitcnt vmcnt(8)
	v_lshlrev_b32_e32 v221, 16, v4
	v_lshlrev_b32_e32 v220, 16, v6
	v_lshlrev_b32_e32 v229, 16, v27
	v_lshlrev_b32_e32 v228, 16, v28
	v_lshlrev_b32_e32 v237, 16, v25
	v_lshlrev_b32_e32 v236, 16, v26
	v_lshlrev_b32_e32 v245, 16, v23
	v_lshlrev_b32_e32 v244, 16, v24
	v_pk_mul_f32 v[222:223], v[220:221], v[220:221]
	v_pk_mul_f32 v[230:231], v[228:229], v[228:229]
	v_pk_mul_f32 v[238:239], v[236:237], v[236:237]
	v_pk_mul_f32 v[246:247], v[244:245], v[244:245]
	ds_bpermute_b32 v223, v9, v223
	ds_bpermute_b32 v222, v9, v222
	ds_bpermute_b32 v231, v9, v231
	ds_bpermute_b32 v230, v9, v230
	ds_bpermute_b32 v239, v9, v239
	ds_bpermute_b32 v238, v9, v238
	ds_bpermute_b32 v247, v9, v247
	ds_bpermute_b32 v246, v9, v246
	v_lshl_add_u64 v[226:227], v[68:69], 0, s[30:31]
	v_lshl_add_u64 v[234:235], v[70:71], 0, s[30:31]
	v_lshl_add_u64 v[242:243], v[68:69], 0, s[28:29]
	v_lshl_add_u64 v[250:251], v[70:71], 0, s[28:29]
	s_waitcnt lgkmcnt(0)
	v_pk_fma_f32 v[222:223], v[220:221], v[220:221], v[222:223]
	v_pk_fma_f32 v[230:231], v[228:229], v[228:229], v[230:231]
	v_pk_fma_f32 v[238:239], v[236:237], v[236:237], v[238:239]
	v_pk_fma_f32 v[246:247], v[244:245], v[244:245], v[246:247]
	ds_bpermute_b32 v225, v10, v223
	ds_bpermute_b32 v224, v10, v222
	ds_bpermute_b32 v233, v10, v231
	ds_bpermute_b32 v232, v10, v230
	ds_bpermute_b32 v241, v10, v239
	ds_bpermute_b32 v240, v10, v238
	ds_bpermute_b32 v249, v10, v247
	ds_bpermute_b32 v248, v10, v246
	s_waitcnt lgkmcnt(0)
	v_pk_add_f32 v[222:223], v[222:223], v[224:225]
	v_pk_add_f32 v[230:231], v[230:231], v[232:233]
	v_pk_add_f32 v[238:239], v[238:239], v[240:241]
	v_pk_add_f32 v[246:247], v[246:247], v[248:249]
	ds_bpermute_b32 v225, v11, v223
	ds_bpermute_b32 v224, v11, v222
	ds_bpermute_b32 v233, v11, v231
	ds_bpermute_b32 v232, v11, v230
	ds_bpermute_b32 v241, v11, v239
	ds_bpermute_b32 v240, v11, v238
	ds_bpermute_b32 v249, v11, v247
	ds_bpermute_b32 v248, v11, v246
	s_waitcnt lgkmcnt(0)
	v_pk_add_f32 v[222:223], v[222:223], v[224:225]
	v_pk_add_f32 v[230:231], v[230:231], v[232:233]
	v_pk_add_f32 v[238:239], v[238:239], v[240:241]
	v_pk_add_f32 v[246:247], v[246:247], v[248:249]
	ds_bpermute_b32 v225, v12, v223
	ds_bpermute_b32 v224, v12, v222
	ds_bpermute_b32 v233, v12, v231
	ds_bpermute_b32 v232, v12, v230
	ds_bpermute_b32 v241, v12, v239
	ds_bpermute_b32 v240, v12, v238
	ds_bpermute_b32 v249, v12, v247
	ds_bpermute_b32 v248, v12, v246
	s_waitcnt lgkmcnt(0)
	v_pk_add_f32 v[222:223], v[222:223], v[224:225]
	v_pk_add_f32 v[230:231], v[230:231], v[232:233]
	v_pk_add_f32 v[238:239], v[238:239], v[240:241]
	v_pk_add_f32 v[246:247], v[246:247], v[248:249]
	ds_bpermute_b32 v225, v13, v223
	ds_bpermute_b32 v224, v13, v222
	ds_bpermute_b32 v233, v13, v231
	ds_bpermute_b32 v232, v13, v230
	ds_bpermute_b32 v241, v13, v239
	ds_bpermute_b32 v240, v13, v238
	ds_bpermute_b32 v249, v13, v247
	ds_bpermute_b32 v248, v13, v246
	s_waitcnt lgkmcnt(0)
	v_pk_add_f32 v[222:223], v[222:223], v[224:225]
	v_pk_add_f32 v[230:231], v[230:231], v[232:233]
	v_pk_add_f32 v[238:239], v[238:239], v[240:241]
	v_pk_add_f32 v[246:247], v[246:247], v[248:249]
	ds_bpermute_b32 v225, v14, v223
	ds_bpermute_b32 v224, v14, v222
	ds_bpermute_b32 v233, v14, v231
	ds_bpermute_b32 v232, v14, v230
	ds_bpermute_b32 v241, v14, v239
	ds_bpermute_b32 v240, v14, v238
	ds_bpermute_b32 v249, v14, v247
	ds_bpermute_b32 v248, v14, v246
	s_waitcnt lgkmcnt(0)
; __device__ __forceinline__ float bf2f(unsigned short u) { return __uint_as_float((unsigned)u << 16); }
; __device__ __forceinline__ unsigned f2bf(float f) { unsigned u = __float_as_uint(f); return (u + 0x7fffu + ((u >> 16) & 1u)) >> 16; }
; __device__ __forceinline__ void knorm_item(const KArgs& a, int l, int item, int wave, int lane) {
;     ...
;         for (int i = 0; i < 16; ++i) { const int task = item * 1024 + wave * 128 + r0 + i, row = task >> 2, which = (task >> 1) & 1, g = task & 1;
;             v[i] = bf2f(Z[(size_t)row * ZW + (which ? ZC_KW : ZC_KS) + g * 64 + lane]); }
;     ...
;         for (int i = 0; i < 16; ++i) { const int task = item * 1024 + wave * 128 + r0 + i, row = task >> 2, which = (task >> 1) & 1, g = task & 1;
;             const float rstd = rsqrtf(wave_sum(v[i] * v[i]) * (1.f / 64.f) + EPS);
;             bf16_t* dst = (bf16_t*)(a.ws + (which ? WS_KWN : WS_KSN));
;             dst[(size_t)row * 128 + g * 64 + lane] = (bf16_t)f2bf(v[i] * rstd * kg); }
	v_pk_add_f32 v[222:223], v[222:223], v[224:225]
	v_pk_add_f32 v[230:231], v[230:231], v[232:233]
	v_pk_add_f32 v[238:239], v[238:239], v[240:241]
	v_pk_add_f32 v[246:247], v[246:247], v[248:249]
	s_nop 0
	v_pk_fma_f32 v[222:223], v[222:223], s[22:23], v[0:1] op_sel_hi:[1,0,0]
	v_pk_fma_f32 v[230:231], v[230:231], s[22:23], v[0:1] op_sel_hi:[1,0,0]
	v_pk_fma_f32 v[238:239], v[238:239], s[22:23], v[0:1] op_sel_hi:[1,0,0]
	v_pk_fma_f32 v[246:247], v[246:247], s[22:23], v[0:1] op_sel_hi:[1,0,0]
	s_nop 0
	v_mul_f32_e32 v224, 0x4b800000, v223
	v_cmp_gt_f32_e64 s[4:5], s48, v223
	v_cmp_gt_f32_e32 vcc, s48, v222
	s_nop 0
	v_cndmask_b32_e64 v223, v223, v224, s[4:5]
	v_rsq_f32_e32 v223, v223
	s_nop 0
	v_mul_f32_e32 v224, 0x45800000, v223
	v_cndmask_b32_e64 v223, v223, v224, s[4:5]
	v_mul_f32_e32 v221, v223, v221
	v_mul_f32_e32 v221, v8, v221
	v_bfe_u32 v223, v221, 16, 1
	v_add3_u32 v221, v221, v223, s49
	global_store_short_d16_hi v[226:227], v221, off
	v_mul_f32_e32 v225, 0x4b800000, v222
	v_cndmask_b32_e32 v225, v222, v225, vcc
	v_rsq_f32_e32 v225, v225
	s_nop 0
	v_mul_f32_e32 v222, 0x45800000, v225
	v_cndmask_b32_e32 v225, v225, v222, vcc
	v_mul_f32_e32 v220, v225, v220
	v_mul_f32_e32 v220, v8, v220
	v_bfe_u32 v225, v220, 16, 1
	v_add3_u32 v220, v220, v225, s49
	global_store_short_d16_hi v[226:227], v220, off offset:128
	v_mul_f32_e32 v232, 0x4b800000, v231
	v_cmp_gt_f32_e64 s[4:5], s48, v231
	v_cmp_gt_f32_e32 vcc, s48, v230
	s_nop 0
	v_cndmask_b32_e64 v231, v231, v232, s[4:5]
	v_rsq_f32_e32 v231, v231
	s_nop 0
	v_mul_f32_e32 v232, 0x45800000, v231
	v_cndmask_b32_e64 v231, v231, v232, s[4:5]
	v_mul_f32_e32 v229, v231, v229
	v_mul_f32_e32 v229, v8, v229
	v_bfe_u32 v231, v229, 16, 1
	v_add3_u32 v229, v229, v231, s49
	global_store_short_d16_hi v[234:235], v229, off
	v_mul_f32_e32 v233, 0x4b800000, v230
	v_cndmask_b32_e32 v233, v230, v233, vcc
	v_rsq_f32_e32 v233, v233
	s_nop 0
	v_mul_f32_e32 v230, 0x45800000, v233
	v_cndmask_b32_e32 v233, v233, v230, vcc
	v_mul_f32_e32 v228, v233, v228
	v_mul_f32_e32 v228, v8, v228
	v_bfe_u32 v233, v228, 16, 1
	v_add3_u32 v228, v228, v233, s49
	global_store_short_d16_hi v[234:235], v228, off offset:128
	v_mul_f32_e32 v240, 0x4b800000, v239
	v_cmp_gt_f32_e64 s[4:5], s48, v239
	v_cmp_gt_f32_e32 vcc, s48, v238
	s_nop 0
	v_cndmask_b32_e64 v239, v239, v240, s[4:5]
	v_rsq_f32_e32 v239, v239
	s_nop 0
	v_mul_f32_e32 v240, 0x45800000, v239
	v_cndmask_b32_e64 v239, v239, v240, s[4:5]
	v_mul_f32_e32 v237, v239, v237
	v_mul_f32_e32 v237, v8, v237
	v_bfe_u32 v239, v237, 16, 1
	v_add3_u32 v237, v237, v239, s49
	global_store_short_d16_hi v[242:243], v237, off
	v_mul_f32_e32 v241, 0x4b800000, v238
	v_cndmask_b32_e32 v241, v238, v241, vcc
	v_rsq_f32_e32 v241, v241
	s_nop 0
	v_mul_f32_e32 v238, 0x45800000, v241
	v_cndmask_b32_e32 v241, v241, v238, vcc
	v_mul_f32_e32 v236, v241, v236
	v_mul_f32_e32 v236, v8, v236
	v_bfe_u32 v241, v236, 16, 1
	v_add3_u32 v236, v236, v241, s49
	global_store_short_d16_hi v[242:243], v236, off offset:128
	v_mul_f32_e32 v248, 0x4b800000, v247
	v_cmp_gt_f32_e64 s[4:5], s48, v247
	v_cmp_gt_f32_e32 vcc, s48, v246
	s_nop 0
	v_cndmask_b32_e64 v247, v247, v248, s[4:5]
	v_rsq_f32_e32 v247, v247
	s_nop 0
	v_mul_f32_e32 v248, 0x45800000, v247
	v_cndmask_b32_e64 v247, v247, v248, s[4:5]
	v_mul_f32_e32 v245, v247, v245
	v_mul_f32_e32 v245, v8, v245
	v_bfe_u32 v247, v245, 16, 1
	v_add3_u32 v245, v245, v247, s49
	global_store_short_d16_hi v[250:251], v245, off
	v_mul_f32_e32 v249, 0x4b800000, v246
	v_cndmask_b32_e32 v249, v246, v249, vcc
	v_rsq_f32_e32 v249, v249
	s_nop 0
	v_mul_f32_e32 v246, 0x45800000, v249
	v_cndmask_b32_e32 v249, v249, v246, vcc
	v_mul_f32_e32 v244, v249, v244
	v_mul_f32_e32 v244, v8, v244
	v_bfe_u32 v249, v244, 16, 1
	v_add3_u32 v244, v244, v249, s49
	global_store_short_d16_hi v[250:251], v244, off offset:128
	s_waitcnt vmcnt(8)
	v_lshlrev_b32_e32 v221, 16, v21
	v_lshlrev_b32_e32 v220, 16, v22
	v_lshlrev_b32_e32 v229, 16, v19
	v_lshlrev_b32_e32 v228, 16, v20
	v_lshlrev_b32_e32 v237, 16, v17
	v_lshlrev_b32_e32 v236, 16, v18
	v_lshlrev_b32_e32 v245, 16, v15
	v_lshlrev_b32_e32 v244, 16, v16
	v_pk_mul_f32 v[222:223], v[220:221], v[220:221]
	v_pk_mul_f32 v[230:231], v[228:229], v[228:229]
	v_pk_mul_f32 v[238:239], v[236:237], v[236:237]
	v_pk_mul_f32 v[246:247], v[244:245], v[244:245]
	ds_bpermute_b32 v223, v9, v223
	ds_bpermute_b32 v222, v9, v222
	ds_bpermute_b32 v231, v9, v231
	ds_bpermute_b32 v230, v9, v230
	ds_bpermute_b32 v239, v9, v239
	ds_bpermute_b32 v238, v9, v238
	ds_bpermute_b32 v247, v9, v247
	ds_bpermute_b32 v246, v9, v246
	v_lshl_add_u64 v[226:227], v[68:69], 0, s[26:27]
	v_lshl_add_u64 v[234:235], v[70:71], 0, s[26:27]
	v_lshl_add_u64 v[242:243], v[68:69], 0, s[0:1]
	v_lshl_add_u64 v[250:251], v[70:71], 0, s[0:1]
	s_waitcnt lgkmcnt(0)
	v_pk_fma_f32 v[222:223], v[220:221], v[220:221], v[222:223]
	v_pk_fma_f32 v[230:231], v[228:229], v[228:229], v[230:231]
	v_pk_fma_f32 v[238:239], v[236:237], v[236:237], v[238:239]
	v_pk_fma_f32 v[246:247], v[244:245], v[244:245], v[246:247]
	ds_bpermute_b32 v225, v10, v223
	ds_bpermute_b32 v224, v10, v222
	ds_bpermute_b32 v233, v10, v231
	ds_bpermute_b32 v232, v10, v230
	ds_bpermute_b32 v241, v10, v239
	ds_bpermute_b32 v240, v10, v238
	ds_bpermute_b32 v249, v10, v247
	ds_bpermute_b32 v248, v10, v246
	s_waitcnt lgkmcnt(0)
	v_pk_add_f32 v[222:223], v[222:223], v[224:225]
	v_pk_add_f32 v[230:231], v[230:231], v[232:233]
	v_pk_add_f32 v[238:239], v[238:239], v[240:241]
	v_pk_add_f32 v[246:247], v[246:247], v[248:249]
	ds_bpermute_b32 v225, v11, v223
	ds_bpermute_b32 v224, v11, v222
	ds_bpermute_b32 v233, v11, v231
	ds_bpermute_b32 v232, v11, v230
	ds_bpermute_b32 v241, v11, v239
	ds_bpermute_b32 v240, v11, v238
	ds_bpermute_b32 v249, v11, v247
	ds_bpermute_b32 v248, v11, v246
	s_waitcnt lgkmcnt(0)
; __device__ __forceinline__ unsigned f2bf(float f) { unsigned u = __float_as_uint(f); return (u + 0x7fffu + ((u >> 16) & 1u)) >> 16; }
; __device__ __forceinline__ void knorm_item(const KArgs& a, int l, int item, int wave, int lane) {
;     ...
;         for (int i = 0; i < 16; ++i) { const int task = item * 1024 + wave * 128 + r0 + i, row = task >> 2, which = (task >> 1) & 1, g = task & 1;
;             const float rstd = rsqrtf(wave_sum(v[i] * v[i]) * (1.f / 64.f) + EPS);
;             bf16_t* dst = (bf16_t*)(a.ws + (which ? WS_KWN : WS_KSN));
;             dst[(size_t)row * 128 + g * 64 + lane] = (bf16_t)f2bf(v[i] * rstd * kg); }
	v_pk_add_f32 v[222:223], v[222:223], v[224:225]
	v_pk_add_f32 v[230:231], v[230:231], v[232:233]
	v_pk_add_f32 v[238:239], v[238:239], v[240:241]
	v_pk_add_f32 v[246:247], v[246:247], v[248:249]
	ds_bpermute_b32 v225, v12, v223
	ds_bpermute_b32 v224, v12, v222
	ds_bpermute_b32 v233, v12, v231
	ds_bpermute_b32 v232, v12, v230
	ds_bpermute_b32 v241, v12, v239
	ds_bpermute_b32 v240, v12, v238
	ds_bpermute_b32 v249, v12, v247
	ds_bpermute_b32 v248, v12, v246
	s_waitcnt lgkmcnt(0)
	v_pk_add_f32 v[222:223], v[222:223], v[224:225]
	v_pk_add_f32 v[230:231], v[230:231], v[232:233]
	v_pk_add_f32 v[238:239], v[238:239], v[240:241]
	v_pk_add_f32 v[246:247], v[246:247], v[248:249]
	ds_bpermute_b32 v225, v13, v223
	ds_bpermute_b32 v224, v13, v222
	ds_bpermute_b32 v233, v13, v231
	ds_bpermute_b32 v232, v13, v230
	ds_bpermute_b32 v241, v13, v239
	ds_bpermute_b32 v240, v13, v238
	ds_bpermute_b32 v249, v13, v247
	ds_bpermute_b32 v248, v13, v246
	s_waitcnt lgkmcnt(0)
	v_pk_add_f32 v[222:223], v[222:223], v[224:225]
	v_pk_add_f32 v[230:231], v[230:231], v[232:233]
	v_pk_add_f32 v[238:239], v[238:239], v[240:241]
	v_pk_add_f32 v[246:247], v[246:247], v[248:249]
	ds_bpermute_b32 v225, v14, v223
	ds_bpermute_b32 v224, v14, v222
	ds_bpermute_b32 v233, v14, v231
	ds_bpermute_b32 v232, v14, v230
	ds_bpermute_b32 v241, v14, v239
	ds_bpermute_b32 v240, v14, v238
	ds_bpermute_b32 v249, v14, v247
	ds_bpermute_b32 v248, v14, v246
	s_waitcnt lgkmcnt(0)
	v_pk_add_f32 v[222:223], v[222:223], v[224:225]
	v_pk_add_f32 v[230:231], v[230:231], v[232:233]
	v_pk_add_f32 v[238:239], v[238:239], v[240:241]
	v_pk_add_f32 v[246:247], v[246:247], v[248:249]
	s_nop 0
	v_pk_fma_f32 v[222:223], v[222:223], s[22:23], v[0:1] op_sel_hi:[1,0,0]
	v_pk_fma_f32 v[230:231], v[230:231], s[22:23], v[0:1] op_sel_hi:[1,0,0]
	v_pk_fma_f32 v[238:239], v[238:239], s[22:23], v[0:1] op_sel_hi:[1,0,0]
	v_pk_fma_f32 v[246:247], v[246:247], s[22:23], v[0:1] op_sel_hi:[1,0,0]
	s_nop 0
	v_mul_f32_e32 v224, 0x4b800000, v223
	v_cmp_gt_f32_e64 s[4:5], s48, v223
	v_cmp_gt_f32_e32 vcc, s48, v222
	s_nop 0
	v_cndmask_b32_e64 v223, v223, v224, s[4:5]
	v_rsq_f32_e32 v223, v223
	s_nop 0
	v_mul_f32_e32 v224, 0x45800000, v223
	v_cndmask_b32_e64 v223, v223, v224, s[4:5]
	v_mul_f32_e32 v221, v223, v221
	v_mul_f32_e32 v221, v8, v221
	v_bfe_u32 v223, v221, 16, 1
	v_add3_u32 v221, v221, v223, s49
	global_store_short_d16_hi v[226:227], v221, off
	v_mul_f32_e32 v225, 0x4b800000, v222
	v_cndmask_b32_e32 v225, v222, v225, vcc
	v_rsq_f32_e32 v225, v225
	s_nop 0
	v_mul_f32_e32 v222, 0x45800000, v225
	v_cndmask_b32_e32 v225, v225, v222, vcc
	v_mul_f32_e32 v220, v225, v220
	v_mul_f32_e32 v220, v8, v220
	v_bfe_u32 v225, v220, 16, 1
	v_add3_u32 v220, v220, v225, s49
	global_store_short_d16_hi v[226:227], v220, off offset:128
	v_mul_f32_e32 v232, 0x4b800000, v231
	v_cmp_gt_f32_e64 s[4:5], s48, v231
	v_cmp_gt_f32_e32 vcc, s48, v230
	s_nop 0
	v_cndmask_b32_e64 v231, v231, v232, s[4:5]
	v_rsq_f32_e32 v231, v231
	s_nop 0
	v_mul_f32_e32 v232, 0x45800000, v231
	v_cndmask_b32_e64 v231, v231, v232, s[4:5]
	v_mul_f32_e32 v229, v231, v229
	v_mul_f32_e32 v229, v8, v229
	v_bfe_u32 v231, v229, 16, 1
	v_add3_u32 v229, v229, v231, s49
	global_store_short_d16_hi v[234:235], v229, off
	v_mul_f32_e32 v233, 0x4b800000, v230
	v_cndmask_b32_e32 v233, v230, v233, vcc
	v_rsq_f32_e32 v233, v233
	s_nop 0
	v_mul_f32_e32 v230, 0x45800000, v233
	v_cndmask_b32_e32 v233, v233, v230, vcc
	v_mul_f32_e32 v228, v233, v228
	v_mul_f32_e32 v228, v8, v228
	v_bfe_u32 v233, v228, 16, 1
	v_add3_u32 v228, v228, v233, s49
	global_store_short_d16_hi v[234:235], v228, off offset:128
	v_mul_f32_e32 v240, 0x4b800000, v239
	v_cmp_gt_f32_e64 s[4:5], s48, v239
	v_cmp_gt_f32_e32 vcc, s48, v238
	s_nop 0
	v_cndmask_b32_e64 v239, v239, v240, s[4:5]
	v_rsq_f32_e32 v239, v239
	s_nop 0
	v_mul_f32_e32 v240, 0x45800000, v239
	v_cndmask_b32_e64 v239, v239, v240, s[4:5]
	v_mul_f32_e32 v237, v239, v237
	v_mul_f32_e32 v237, v8, v237
	v_bfe_u32 v239, v237, 16, 1
	v_add3_u32 v237, v237, v239, s49
	global_store_short_d16_hi v[242:243], v237, off
	v_mul_f32_e32 v241, 0x4b800000, v238
	v_cndmask_b32_e32 v241, v238, v241, vcc
	v_rsq_f32_e32 v241, v241
	s_nop 0
	v_mul_f32_e32 v238, 0x45800000, v241
	v_cndmask_b32_e32 v241, v241, v238, vcc
	v_mul_f32_e32 v236, v241, v236
	v_mul_f32_e32 v236, v8, v236
	v_bfe_u32 v241, v236, 16, 1
	v_add3_u32 v236, v236, v241, s49
	global_store_short_d16_hi v[242:243], v236, off offset:128
	v_mul_f32_e32 v248, 0x4b800000, v247
	v_cmp_gt_f32_e64 s[4:5], s48, v247
	v_cmp_gt_f32_e32 vcc, s48, v246
	s_nop 0
	v_cndmask_b32_e64 v247, v247, v248, s[4:5]
	v_rsq_f32_e32 v247, v247
	s_nop 0
	v_mul_f32_e32 v248, 0x45800000, v247
	v_cndmask_b32_e64 v247, v247, v248, s[4:5]
	v_mul_f32_e32 v245, v247, v245
	v_mul_f32_e32 v245, v8, v245
	v_bfe_u32 v247, v245, 16, 1
	v_add3_u32 v245, v245, v247, s49
	global_store_short_d16_hi v[250:251], v245, off
	v_mul_f32_e32 v249, 0x4b800000, v246
	v_cndmask_b32_e32 v249, v246, v249, vcc
	v_rsq_f32_e32 v249, v249
	s_nop 0
	v_mul_f32_e32 v246, 0x45800000, v249
	v_cndmask_b32_e32 v249, v249, v246, vcc
	v_mul_f32_e32 v244, v249, v244
	v_mul_f32_e32 v244, v8, v244
	v_bfe_u32 v249, v244, 16, 1
	v_add3_u32 v244, v244, v249, s49
	global_store_short_d16_hi v[250:251], v244, off offset:128
	s_cbranch_scc0 .LBB0_237
	s_mov_b64 s[0:1], 0

; __device__ __forceinline__ float bf2f(unsigned short u) { return __uint_as_float((unsigned)u << 16); }
; __device__ __forceinline__ void knorm_item(const KArgs& a, int l, int item, int wave, int lane) {
;     ...
;     for (int r0 = 0; r0 < 128; r0 += 16) {
;         float v[16];
; #pragma unroll
;         for (int i = 0; i < 16; ++i) { const int task = item * 1024 + wave * 128 + r0 + i, row = task >> 2, which = (task >> 1) & 1, g = task & 1;
;             v[i] = bf2f(Z[(size_t)row * ZW + (which ? ZC_KW : ZC_KS) + g * 64 + lane]); }
; #pragma unroll
;         for (int i = 0; i < 16; ++i) { const int task = item * 1024 + wave * 128 + r0 + i, row = task >> 2, which = (task >> 1) & 1, g = task & 1;
;             const float rstd = rsqrtf(wave_sum(v[i] * v[i]) * (1.f / 64.f) + EPS);
.LBB0_1038:
	s_add_i32 s0, s30, s63
	s_add_i32 s0, s0, 0xfff80010
	s_ashr_i32 s4, s0, 2
	s_ashr_i32 s5, s4, 31
	s_mul_i32 s0, s4, 0x1a00
	s_mul_hi_i32 s1, s4, 0x1a00
	s_add_u32 s0, s92, s0
	s_addc_u32 s1, s93, s1
	v_lshl_add_u64 v[0:1], s[0:1], 0, v[64:65]
	v_add_co_u32_e32 v0, vcc, s53, v0
	s_or_b32 s36, s4, 1
	s_nop 0
	v_addc_co_u32_e32 v1, vcc, 0, v1, vcc
	global_load_ushort v4, v[0:1], off offset:1024
	global_load_ushort v6, v[0:1], off offset:1152
	global_load_ushort v27, v[0:1], off offset:1536
	global_load_ushort v28, v[0:1], off offset:1664
	s_ashr_i32 s37, s36, 31
	s_mul_i32 s0, s36, 0x1a00
	s_mul_hi_i32 s1, s36, 0x1a00
	s_add_u32 s0, s92, s0
	s_addc_u32 s1, s93, s1
	s_or_b32 s34, s4, 2
	v_lshl_add_u64 v[0:1], s[0:1], 0, v[64:65]
	s_ashr_i32 s35, s34, 31
	s_mul_i32 s0, s34, 0x1a00
	v_add_co_u32_e32 v0, vcc, s53, v0
	s_mul_hi_i32 s1, s34, 0x1a00
	s_add_u32 s0, s92, s0
	v_addc_co_u32_e32 v1, vcc, 0, v1, vcc
	s_addc_u32 s1, s93, s1
	global_load_ushort v25, v[0:1], off offset:1024
	global_load_ushort v26, v[0:1], off offset:1152
	global_load_ushort v23, v[0:1], off offset:1536
	global_load_ushort v24, v[0:1], off offset:1664
	v_lshl_add_u64 v[0:1], s[0:1], 0, v[64:65]
	s_or_b32 s0, s4, 3
	s_ashr_i32 s1, s0, 31
	s_mul_i32 s38, s0, 0x1a00
	v_add_co_u32_e32 v0, vcc, s53, v0
	s_mul_hi_i32 s39, s0, 0x1a00
	s_add_u32 s38, s92, s38
	v_addc_co_u32_e32 v1, vcc, 0, v1, vcc
	s_addc_u32 s39, s93, s39
	global_load_ushort v21, v[0:1], off offset:1024
	global_load_ushort v22, v[0:1], off offset:1152
	global_load_ushort v19, v[0:1], off offset:1536
	global_load_ushort v20, v[0:1], off offset:1664
	v_lshl_add_u64 v[0:1], s[38:39], 0, v[64:65]
	v_add_co_u32_e32 v0, vcc, s53, v0
	s_lshl_b64 s[38:39], s[4:5], 8
	s_nop 0
	v_addc_co_u32_e32 v1, vcc, 0, v1, vcc
	global_load_ushort v17, v[0:1], off offset:1024
	global_load_ushort v18, v[0:1], off offset:1152
	global_load_ushort v15, v[0:1], off offset:1536
	global_load_ushort v16, v[0:1], off offset:1664
	v_lshl_add_u64 v[2:3], v[68:69], 0, s[38:39]
	s_lshl_b64 s[36:37], s[36:37], 8
	s_lshl_b64 s[34:35], s[34:35], 8
	s_lshl_b64 s[0:1], s[0:1], 8
	s_add_i32 s63, s63, 16
	s_cmpk_gt_u32 s63, 0x6f
	v_mov_b64_e32 v[0:1], s[26:27]
	s_waitcnt vmcnt(8)
	v_lshlrev_b32_e32 v221, 16, v4
	v_lshlrev_b32_e32 v220, 16, v6
	v_lshlrev_b32_e32 v229, 16, v27
	v_lshlrev_b32_e32 v228, 16, v28
	v_lshlrev_b32_e32 v237, 16, v25
	v_lshlrev_b32_e32 v236, 16, v26
	v_lshlrev_b32_e32 v245, 16, v23
	v_lshlrev_b32_e32 v244, 16, v24
	v_pk_mul_f32 v[222:223], v[220:221], v[220:221]
	v_pk_mul_f32 v[230:231], v[228:229], v[228:229]
	v_pk_mul_f32 v[238:239], v[236:237], v[236:237]
	v_pk_mul_f32 v[246:247], v[244:245], v[244:245]
	ds_bpermute_b32 v223, v9, v223
	ds_bpermute_b32 v222, v9, v222
	ds_bpermute_b32 v231, v9, v231
	ds_bpermute_b32 v230, v9, v230
	ds_bpermute_b32 v239, v9, v239
	ds_bpermute_b32 v238, v9, v238
	ds_bpermute_b32 v247, v9, v247
	ds_bpermute_b32 v246, v9, v246
	v_lshl_add_u64 v[226:227], v[68:69], 0, s[38:39]
	v_lshl_add_u64 v[234:235], v[70:71], 0, s[38:39]
	v_lshl_add_u64 v[242:243], v[68:69], 0, s[36:37]
	v_lshl_add_u64 v[250:251], v[70:71], 0, s[36:37]
	s_waitcnt lgkmcnt(0)
	v_pk_fma_f32 v[222:223], v[220:221], v[220:221], v[222:223]
	v_pk_fma_f32 v[230:231], v[228:229], v[228:229], v[230:231]
	v_pk_fma_f32 v[238:239], v[236:237], v[236:237], v[238:239]
	v_pk_fma_f32 v[246:247], v[244:245], v[244:245], v[246:247]
	ds_bpermute_b32 v225, v10, v223
	ds_bpermute_b32 v224, v10, v222
	ds_bpermute_b32 v233, v10, v231
	ds_bpermute_b32 v232, v10, v230
	ds_bpermute_b32 v241, v10, v239
	ds_bpermute_b32 v240, v10, v238
	ds_bpermute_b32 v249, v10, v247
	ds_bpermute_b32 v248, v10, v246
	s_waitcnt lgkmcnt(0)
	v_pk_add_f32 v[222:223], v[222:223], v[224:225]
	v_pk_add_f32 v[230:231], v[230:231], v[232:233]
	v_pk_add_f32 v[238:239], v[238:239], v[240:241]
	v_pk_add_f32 v[246:247], v[246:247], v[248:249]
	ds_bpermute_b32 v225, v11, v223
	ds_bpermute_b32 v224, v11, v222
	ds_bpermute_b32 v233, v11, v231
	ds_bpermute_b32 v232, v11, v230
	ds_bpermute_b32 v241, v11, v239
	ds_bpermute_b32 v240, v11, v238
	ds_bpermute_b32 v249, v11, v247
	ds_bpermute_b32 v248, v11, v246
	s_waitcnt lgkmcnt(0)
	v_pk_add_f32 v[222:223], v[222:223], v[224:225]
	v_pk_add_f32 v[230:231], v[230:231], v[232:233]
	v_pk_add_f32 v[238:239], v[238:239], v[240:241]
	v_pk_add_f32 v[246:247], v[246:247], v[248:249]
	ds_bpermute_b32 v225, v12, v223
	ds_bpermute_b32 v224, v12, v222
	ds_bpermute_b32 v233, v12, v231
	ds_bpermute_b32 v232, v12, v230
	ds_bpermute_b32 v241, v12, v239
	ds_bpermute_b32 v240, v12, v238
	ds_bpermute_b32 v249, v12, v247
	ds_bpermute_b32 v248, v12, v246
	s_waitcnt lgkmcnt(0)
	v_pk_add_f32 v[222:223], v[222:223], v[224:225]
	v_pk_add_f32 v[230:231], v[230:231], v[232:233]
	v_pk_add_f32 v[238:239], v[238:239], v[240:241]
	v_pk_add_f32 v[246:247], v[246:247], v[248:249]
	ds_bpermute_b32 v225, v13, v223
	ds_bpermute_b32 v224, v13, v222
	ds_bpermute_b32 v233, v13, v231
	ds_bpermute_b32 v232, v13, v230
	ds_bpermute_b32 v241, v13, v239
	ds_bpermute_b32 v240, v13, v238
	ds_bpermute_b32 v249, v13, v247
	ds_bpermute_b32 v248, v13, v246
	s_waitcnt lgkmcnt(0)
	v_pk_add_f32 v[222:223], v[222:223], v[224:225]
	v_pk_add_f32 v[230:231], v[230:231], v[232:233]
	v_pk_add_f32 v[238:239], v[238:239], v[240:241]
	v_pk_add_f32 v[246:247], v[246:247], v[248:249]
	ds_bpermute_b32 v225, v14, v223
	ds_bpermute_b32 v224, v14, v222
	ds_bpermute_b32 v233, v14, v231
	ds_bpermute_b32 v232, v14, v230
	ds_bpermute_b32 v241, v14, v239
	ds_bpermute_b32 v240, v14, v238
	ds_bpermute_b32 v249, v14, v247
	ds_bpermute_b32 v248, v14, v246
	s_waitcnt lgkmcnt(0)
; __device__ __forceinline__ float bf2f(unsigned short u) { return __uint_as_float((unsigned)u << 16); }
; __device__ __forceinline__ unsigned f2bf(float f) { unsigned u = __float_as_uint(f); return (u + 0x7fffu + ((u >> 16) & 1u)) >> 16; }
; __device__ __forceinline__ void knorm_item(const KArgs& a, int l, int item, int wave, int lane) {
;     ...
;         for (int i = 0; i < 16; ++i) { const int task = item * 1024 + wave * 128 + r0 + i, row = task >> 2, which = (task >> 1) & 1, g = task & 1;
;             v[i] = bf2f(Z[(size_t)row * ZW + (which ? ZC_KW : ZC_KS) + g * 64 + lane]); }
;     ...
;         for (int i = 0; i < 16; ++i) { const int task = item * 1024 + wave * 128 + r0 + i, row = task >> 2, which = (task >> 1) & 1, g = task & 1;
;             const float rstd = rsqrtf(wave_sum(v[i] * v[i]) * (1.f / 64.f) + EPS);
;             bf16_t* dst = (bf16_t*)(a.ws + (which ? WS_KWN : WS_KSN));
;             dst[(size_t)row * 128 + g * 64 + lane] = (bf16_t)f2bf(v[i] * rstd * kg); }
	v_pk_add_f32 v[222:223], v[222:223], v[224:225]
	v_pk_add_f32 v[230:231], v[230:231], v[232:233]
	v_pk_add_f32 v[238:239], v[238:239], v[240:241]
	v_pk_add_f32 v[246:247], v[246:247], v[248:249]
	s_nop 0
	v_pk_fma_f32 v[222:223], v[222:223], s[28:29], v[0:1] op_sel_hi:[1,0,0]
	v_pk_fma_f32 v[230:231], v[230:231], s[28:29], v[0:1] op_sel_hi:[1,0,0]
	v_pk_fma_f32 v[238:239], v[238:239], s[28:29], v[0:1] op_sel_hi:[1,0,0]
	v_pk_fma_f32 v[246:247], v[246:247], s[28:29], v[0:1] op_sel_hi:[1,0,0]
	s_nop 0
	v_mul_f32_e32 v224, 0x4b800000, v223
	v_cmp_gt_f32_e64 s[4:5], s54, v223
	v_cmp_gt_f32_e32 vcc, s54, v222
	s_nop 0
	v_cndmask_b32_e64 v223, v223, v224, s[4:5]
	v_rsq_f32_e32 v223, v223
	s_nop 0
	v_mul_f32_e32 v224, 0x45800000, v223
	v_cndmask_b32_e64 v223, v223, v224, s[4:5]
	v_mul_f32_e32 v221, v223, v221
	v_mul_f32_e32 v221, v8, v221
	v_bfe_u32 v223, v221, 16, 1
	v_add3_u32 v221, v221, v223, s55
	global_store_short_d16_hi v[226:227], v221, off
	v_mul_f32_e32 v225, 0x4b800000, v222
	v_cndmask_b32_e32 v225, v222, v225, vcc
	v_rsq_f32_e32 v225, v225
	s_nop 0
	v_mul_f32_e32 v222, 0x45800000, v225
	v_cndmask_b32_e32 v225, v225, v222, vcc
	v_mul_f32_e32 v220, v225, v220
	v_mul_f32_e32 v220, v8, v220
	v_bfe_u32 v225, v220, 16, 1
	v_add3_u32 v220, v220, v225, s55
	global_store_short_d16_hi v[226:227], v220, off offset:128
	v_mul_f32_e32 v232, 0x4b800000, v231
	v_cmp_gt_f32_e64 s[4:5], s54, v231
	v_cmp_gt_f32_e32 vcc, s54, v230
	s_nop 0
	v_cndmask_b32_e64 v231, v231, v232, s[4:5]
	v_rsq_f32_e32 v231, v231
	s_nop 0
	v_mul_f32_e32 v232, 0x45800000, v231
	v_cndmask_b32_e64 v231, v231, v232, s[4:5]
	v_mul_f32_e32 v229, v231, v229
	v_mul_f32_e32 v229, v8, v229
	v_bfe_u32 v231, v229, 16, 1
	v_add3_u32 v229, v229, v231, s55
	global_store_short_d16_hi v[234:235], v229, off
	v_mul_f32_e32 v233, 0x4b800000, v230
	v_cndmask_b32_e32 v233, v230, v233, vcc
	v_rsq_f32_e32 v233, v233
	s_nop 0
	v_mul_f32_e32 v230, 0x45800000, v233
	v_cndmask_b32_e32 v233, v233, v230, vcc
	v_mul_f32_e32 v228, v233, v228
	v_mul_f32_e32 v228, v8, v228
	v_bfe_u32 v233, v228, 16, 1
	v_add3_u32 v228, v228, v233, s55
	global_store_short_d16_hi v[234:235], v228, off offset:128
	v_mul_f32_e32 v240, 0x4b800000, v239
	v_cmp_gt_f32_e64 s[4:5], s54, v239
	v_cmp_gt_f32_e32 vcc, s54, v238
	s_nop 0
	v_cndmask_b32_e64 v239, v239, v240, s[4:5]
	v_rsq_f32_e32 v239, v239
	s_nop 0
	v_mul_f32_e32 v240, 0x45800000, v239
	v_cndmask_b32_e64 v239, v239, v240, s[4:5]
	v_mul_f32_e32 v237, v239, v237
	v_mul_f32_e32 v237, v8, v237
	v_bfe_u32 v239, v237, 16, 1
	v_add3_u32 v237, v237, v239, s55
	global_store_short_d16_hi v[242:243], v237, off
	v_mul_f32_e32 v241, 0x4b800000, v238
	v_cndmask_b32_e32 v241, v238, v241, vcc
	v_rsq_f32_e32 v241, v241
	s_nop 0
	v_mul_f32_e32 v238, 0x45800000, v241
	v_cndmask_b32_e32 v241, v241, v238, vcc
	v_mul_f32_e32 v236, v241, v236
	v_mul_f32_e32 v236, v8, v236
	v_bfe_u32 v241, v236, 16, 1
	v_add3_u32 v236, v236, v241, s55
	global_store_short_d16_hi v[242:243], v236, off offset:128
	v_mul_f32_e32 v248, 0x4b800000, v247
	v_cmp_gt_f32_e64 s[4:5], s54, v247
	v_cmp_gt_f32_e32 vcc, s54, v246
	s_nop 0
	v_cndmask_b32_e64 v247, v247, v248, s[4:5]
	v_rsq_f32_e32 v247, v247
	s_nop 0
	v_mul_f32_e32 v248, 0x45800000, v247
	v_cndmask_b32_e64 v247, v247, v248, s[4:5]
	v_mul_f32_e32 v245, v247, v245
	v_mul_f32_e32 v245, v8, v245
	v_bfe_u32 v247, v245, 16, 1
	v_add3_u32 v245, v245, v247, s55
	global_store_short_d16_hi v[250:251], v245, off
	v_mul_f32_e32 v249, 0x4b800000, v246
	v_cndmask_b32_e32 v249, v246, v249, vcc
	v_rsq_f32_e32 v249, v249
	s_nop 0
	v_mul_f32_e32 v246, 0x45800000, v249
	v_cndmask_b32_e32 v249, v249, v246, vcc
	v_mul_f32_e32 v244, v249, v244
	v_mul_f32_e32 v244, v8, v244
	v_bfe_u32 v249, v244, 16, 1
	v_add3_u32 v244, v244, v249, s55
	global_store_short_d16_hi v[250:251], v244, off offset:128
	s_waitcnt vmcnt(8)
	v_lshlrev_b32_e32 v221, 16, v21
	v_lshlrev_b32_e32 v220, 16, v22
	v_lshlrev_b32_e32 v229, 16, v19
	v_lshlrev_b32_e32 v228, 16, v20
	v_lshlrev_b32_e32 v237, 16, v17
	v_lshlrev_b32_e32 v236, 16, v18
	v_lshlrev_b32_e32 v245, 16, v15
	v_lshlrev_b32_e32 v244, 16, v16
	v_pk_mul_f32 v[222:223], v[220:221], v[220:221]
	v_pk_mul_f32 v[230:231], v[228:229], v[228:229]
	v_pk_mul_f32 v[238:239], v[236:237], v[236:237]
	v_pk_mul_f32 v[246:247], v[244:245], v[244:245]
	ds_bpermute_b32 v223, v9, v223
	ds_bpermute_b32 v222, v9, v222
	ds_bpermute_b32 v231, v9, v231
	ds_bpermute_b32 v230, v9, v230
	ds_bpermute_b32 v239, v9, v239
	ds_bpermute_b32 v238, v9, v238
	ds_bpermute_b32 v247, v9, v247
	ds_bpermute_b32 v246, v9, v246
	v_lshl_add_u64 v[226:227], v[68:69], 0, s[34:35]
	v_lshl_add_u64 v[234:235], v[70:71], 0, s[34:35]
	v_lshl_add_u64 v[242:243], v[68:69], 0, s[0:1]
	v_lshl_add_u64 v[250:251], v[70:71], 0, s[0:1]
	s_waitcnt lgkmcnt(0)
	v_pk_fma_f32 v[222:223], v[220:221], v[220:221], v[222:223]
	v_pk_fma_f32 v[230:231], v[228:229], v[228:229], v[230:231]
	v_pk_fma_f32 v[238:239], v[236:237], v[236:237], v[238:239]
	v_pk_fma_f32 v[246:247], v[244:245], v[244:245], v[246:247]
	ds_bpermute_b32 v225, v10, v223
	ds_bpermute_b32 v224, v10, v222
	ds_bpermute_b32 v233, v10, v231
	ds_bpermute_b32 v232, v10, v230
	ds_bpermute_b32 v241, v10, v239
	ds_bpermute_b32 v240, v10, v238
	ds_bpermute_b32 v249, v10, v247
	ds_bpermute_b32 v248, v10, v246
	s_waitcnt lgkmcnt(0)
	v_pk_add_f32 v[222:223], v[222:223], v[224:225]
	v_pk_add_f32 v[230:231], v[230:231], v[232:233]
	v_pk_add_f32 v[238:239], v[238:239], v[240:241]
	v_pk_add_f32 v[246:247], v[246:247], v[248:249]
	ds_bpermute_b32 v225, v11, v223
	ds_bpermute_b32 v224, v11, v222
	ds_bpermute_b32 v233, v11, v231
	ds_bpermute_b32 v232, v11, v230
	ds_bpermute_b32 v241, v11, v239
	ds_bpermute_b32 v240, v11, v238
	ds_bpermute_b32 v249, v11, v247
	ds_bpermute_b32 v248, v11, v246
	s_waitcnt lgkmcnt(0)
; __device__ __forceinline__ unsigned f2bf(float f) { unsigned u = __float_as_uint(f); return (u + 0x7fffu + ((u >> 16) & 1u)) >> 16; }
; __device__ __forceinline__ void knorm_item(const KArgs& a, int l, int item, int wave, int lane) {
;     ...
;         for (int i = 0; i < 16; ++i) { const int task = item * 1024 + wave * 128 + r0 + i, row = task >> 2, which = (task >> 1) & 1, g = task & 1;
;             const float rstd = rsqrtf(wave_sum(v[i] * v[i]) * (1.f / 64.f) + EPS);
;             bf16_t* dst = (bf16_t*)(a.ws + (which ? WS_KWN : WS_KSN));
;             dst[(size_t)row * 128 + g * 64 + lane] = (bf16_t)f2bf(v[i] * rstd * kg); }
	v_pk_add_f32 v[222:223], v[222:223], v[224:225]
	v_pk_add_f32 v[230:231], v[230:231], v[232:233]
	v_pk_add_f32 v[238:239], v[238:239], v[240:241]
	v_pk_add_f32 v[246:247], v[246:247], v[248:249]
	ds_bpermute_b32 v225, v12, v223
	ds_bpermute_b32 v224, v12, v222
	ds_bpermute_b32 v233, v12, v231
	ds_bpermute_b32 v232, v12, v230
	ds_bpermute_b32 v241, v12, v239
	ds_bpermute_b32 v240, v12, v238
	ds_bpermute_b32 v249, v12, v247
	ds_bpermute_b32 v248, v12, v246
	s_waitcnt lgkmcnt(0)
	v_pk_add_f32 v[222:223], v[222:223], v[224:225]
	v_pk_add_f32 v[230:231], v[230:231], v[232:233]
	v_pk_add_f32 v[238:239], v[238:239], v[240:241]
	v_pk_add_f32 v[246:247], v[246:247], v[248:249]
	ds_bpermute_b32 v225, v13, v223
	ds_bpermute_b32 v224, v13, v222
	ds_bpermute_b32 v233, v13, v231
	ds_bpermute_b32 v232, v13, v230
	ds_bpermute_b32 v241, v13, v239
	ds_bpermute_b32 v240, v13, v238
	ds_bpermute_b32 v249, v13, v247
	ds_bpermute_b32 v248, v13, v246
	s_waitcnt lgkmcnt(0)
	v_pk_add_f32 v[222:223], v[222:223], v[224:225]
	v_pk_add_f32 v[230:231], v[230:231], v[232:233]
	v_pk_add_f32 v[238:239], v[238:239], v[240:241]
	v_pk_add_f32 v[246:247], v[246:247], v[248:249]
	ds_bpermute_b32 v225, v14, v223
	ds_bpermute_b32 v224, v14, v222
	ds_bpermute_b32 v233, v14, v231
	ds_bpermute_b32 v232, v14, v230
	ds_bpermute_b32 v241, v14, v239
	ds_bpermute_b32 v240, v14, v238
	ds_bpermute_b32 v249, v14, v247
	ds_bpermute_b32 v248, v14, v246
	s_waitcnt lgkmcnt(0)
	v_pk_add_f32 v[222:223], v[222:223], v[224:225]
	v_pk_add_f32 v[230:231], v[230:231], v[232:233]
	v_pk_add_f32 v[238:239], v[238:239], v[240:241]
	v_pk_add_f32 v[246:247], v[246:247], v[248:249]
	s_nop 0
	v_pk_fma_f32 v[222:223], v[222:223], s[28:29], v[0:1] op_sel_hi:[1,0,0]
	v_pk_fma_f32 v[230:231], v[230:231], s[28:29], v[0:1] op_sel_hi:[1,0,0]
	v_pk_fma_f32 v[238:239], v[238:239], s[28:29], v[0:1] op_sel_hi:[1,0,0]
	v_pk_fma_f32 v[246:247], v[246:247], s[28:29], v[0:1] op_sel_hi:[1,0,0]
	s_nop 0
	v_mul_f32_e32 v224, 0x4b800000, v223
	v_cmp_gt_f32_e64 s[4:5], s54, v223
	v_cmp_gt_f32_e32 vcc, s54, v222
	s_nop 0
	v_cndmask_b32_e64 v223, v223, v224, s[4:5]
	v_rsq_f32_e32 v223, v223
	s_nop 0
	v_mul_f32_e32 v224, 0x45800000, v223
	v_cndmask_b32_e64 v223, v223, v224, s[4:5]
	v_mul_f32_e32 v221, v223, v221
	v_mul_f32_e32 v221, v8, v221
	v_bfe_u32 v223, v221, 16, 1
	v_add3_u32 v221, v221, v223, s55
	global_store_short_d16_hi v[226:227], v221, off
	v_mul_f32_e32 v225, 0x4b800000, v222
	v_cndmask_b32_e32 v225, v222, v225, vcc
	v_rsq_f32_e32 v225, v225
	s_nop 0
	v_mul_f32_e32 v222, 0x45800000, v225
	v_cndmask_b32_e32 v225, v225, v222, vcc
	v_mul_f32_e32 v220, v225, v220
	v_mul_f32_e32 v220, v8, v220
	v_bfe_u32 v225, v220, 16, 1
	v_add3_u32 v220, v220, v225, s55
	global_store_short_d16_hi v[226:227], v220, off offset:128
	v_mul_f32_e32 v232, 0x4b800000, v231
	v_cmp_gt_f32_e64 s[4:5], s54, v231
	v_cmp_gt_f32_e32 vcc, s54, v230
	s_nop 0
	v_cndmask_b32_e64 v231, v231, v232, s[4:5]
	v_rsq_f32_e32 v231, v231
	s_nop 0
	v_mul_f32_e32 v232, 0x45800000, v231
	v_cndmask_b32_e64 v231, v231, v232, s[4:5]
	v_mul_f32_e32 v229, v231, v229
	v_mul_f32_e32 v229, v8, v229
	v_bfe_u32 v231, v229, 16, 1
	v_add3_u32 v229, v229, v231, s55
	global_store_short_d16_hi v[234:235], v229, off
	v_mul_f32_e32 v233, 0x4b800000, v230
	v_cndmask_b32_e32 v233, v230, v233, vcc
	v_rsq_f32_e32 v233, v233
	s_nop 0
	v_mul_f32_e32 v230, 0x45800000, v233
	v_cndmask_b32_e32 v233, v233, v230, vcc
	v_mul_f32_e32 v228, v233, v228
	v_mul_f32_e32 v228, v8, v228
	v_bfe_u32 v233, v228, 16, 1
	v_add3_u32 v228, v228, v233, s55
	global_store_short_d16_hi v[234:235], v228, off offset:128
	v_mul_f32_e32 v240, 0x4b800000, v239
	v_cmp_gt_f32_e64 s[4:5], s54, v239
	v_cmp_gt_f32_e32 vcc, s54, v238
	s_nop 0
	v_cndmask_b32_e64 v239, v239, v240, s[4:5]
	v_rsq_f32_e32 v239, v239
	s_nop 0
	v_mul_f32_e32 v240, 0x45800000, v239
	v_cndmask_b32_e64 v239, v239, v240, s[4:5]
	v_mul_f32_e32 v237, v239, v237
	v_mul_f32_e32 v237, v8, v237
	v_bfe_u32 v239, v237, 16, 1
	v_add3_u32 v237, v237, v239, s55
	global_store_short_d16_hi v[242:243], v237, off
	v_mul_f32_e32 v241, 0x4b800000, v238
	v_cndmask_b32_e32 v241, v238, v241, vcc
	v_rsq_f32_e32 v241, v241
	s_nop 0
	v_mul_f32_e32 v238, 0x45800000, v241
	v_cndmask_b32_e32 v241, v241, v238, vcc
	v_mul_f32_e32 v236, v241, v236
	v_mul_f32_e32 v236, v8, v236
	v_bfe_u32 v241, v236, 16, 1
	v_add3_u32 v236, v236, v241, s55
	global_store_short_d16_hi v[242:243], v236, off offset:128
	v_mul_f32_e32 v248, 0x4b800000, v247
	v_cmp_gt_f32_e64 s[4:5], s54, v247
	v_cmp_gt_f32_e32 vcc, s54, v246
	s_nop 0
	v_cndmask_b32_e64 v247, v247, v248, s[4:5]
	v_rsq_f32_e32 v247, v247
	s_nop 0
	v_mul_f32_e32 v248, 0x45800000, v247
	v_cndmask_b32_e64 v247, v247, v248, s[4:5]
	v_mul_f32_e32 v245, v247, v245
	v_mul_f32_e32 v245, v8, v245
	v_bfe_u32 v247, v245, 16, 1
	v_add3_u32 v245, v245, v247, s55
	global_store_short_d16_hi v[250:251], v245, off
	v_mul_f32_e32 v249, 0x4b800000, v246
	v_cndmask_b32_e32 v249, v246, v249, vcc
	v_rsq_f32_e32 v249, v249
	s_nop 0
	v_mul_f32_e32 v246, 0x45800000, v249
	v_cndmask_b32_e32 v249, v249, v246, vcc
	v_mul_f32_e32 v244, v249, v244
	v_mul_f32_e32 v244, v8, v244
	v_bfe_u32 v249, v244, 16, 1
	v_add3_u32 v244, v244, v249, s55
	global_store_short_d16_hi v[250:251], v244, off offset:128
	s_cbranch_scc0 .LBB0_1038
	s_mov_b64 s[0:1], 0
